# GEMM K-loops: per-phase s_setprio flips removed, one static s_setprio 1 for waves 4-7 during P2 and P6
# speedup vs baseline: 1.0040x; 1.0040x over previous
.LBB0_189:
	s_cmp_ge_u32 s3, 4
	s_cbranch_scc0 .Lprio_skip0
	s_setprio 1
.Lprio_skip0:
	s_cmp_lt_i32 s80, 3
	s_cselect_b64 s[0:1], -1, 0
	s_cmp_gt_i32 s81, 2
	s_cselect_b64 s[4:5], -1, 0
	s_and_b64 s[0:1], s[0:1], s[4:5]
	s_andn2_b64 vcc, exec, s[0:1]
	s_cbranch_vccnz .LBB0_294
	s_cmpk_lt_i32 s2, 0x900
	s_cselect_b64 s[0:1], -1, 0
	s_cmpk_gt_i32 s2, 0x8ff
	s_waitcnt lgkmcnt(0)
	v_readfirstlane_b32 s16, v144
	s_cbranch_scc1 .LBB0_193
	s_ashr_i32 s4, s2, 31
	s_lshr_b32 s4, s4, 29
	s_add_i32 s4, s2, s4
	s_ashr_i32 s5, s4, 3
	s_and_b32 s4, s4, -8
	s_sub_i32 s4, s2, s4
	s_cmp_lt_i32 s4, 0
	s_movk_i32 s6, 0x121
	s_cselect_b32 s6, s6, 0x120
	s_mul_i32 s4, s4, s6
	s_add_i32 s4, s4, s5
	s_mul_hi_i32 s5, s4, 0x38e38e39
	s_lshr_b32 s6, s5, 31
	s_ashr_i32 s5, s5, 5
	s_add_i32 s5, s5, s6
	s_lshl_b32 s6, s5, 3
	s_mulk_i32 s5, 0x90
	s_sub_i32 s4, s4, s5
	s_bfe_u32 s5, s4, 0x3001c
	s_add_i32 s5, s4, s5
	s_sext_i32_i16 s7, s5
	s_and_b32 s5, s5, 0xfff8
	s_sub_i32 s4, s4, s5
	s_sext_i32_i16 s4, s4
	s_add_i32 s26, s6, s4
	s_ashr_i32 s4, s7, 3
	s_andn2_b64 vcc, exec, s[0:1]
	s_cbranch_vccz .LBB0_194

.LBB0_202:
	ds_read_b128 v[52:55], v171
	ds_read_b128 v[60:63], v171 offset:1024
	ds_read_b128 v[64:67], v171 offset:2048
	ds_read_b128 v[72:75], v171 offset:3072
	ds_read_b128 v[164:167], v172
	ds_read_b128 v[176:179], v172 offset:1024
	ds_read_b128 v[180:183], v172 offset:2048
	ds_read_b128 v[184:187], v172 offset:3072
	s_add_u32 s30, s28, 0xfff80080
	s_addc_u32 s31, s29, -1
	s_cmp_eq_u32 s75, 28
	s_cselect_b32 s35, s5, s31
	s_cselect_b32 s34, s21, s30
	s_cselect_b32 s31, s19, s74
	s_cselect_b32 s30, s72, s73
	v_lshl_add_u64 v[168:169], s[28:29], 0, v[156:157]
	s_add_i32 m0, s27, 0xc000
	ds_read_b128 v[188:191], v173
	ds_read_b128 v[194:197], v173 offset:1024
	ds_read_b128 v[198:201], v173 offset:2048
	ds_read_b128 v[202:205], v173 offset:3072
	ds_read_b128 v[206:209], v173 offset:4096
	ds_read_b128 v[210:213], v173 offset:5120
	ds_read_b128 v[214:217], v173 offset:6144
	ds_read_b128 v[218:221], v173 offset:7168
	global_load_lds_dwordx4 v[168:169], off
	v_lshl_add_u64 v[168:169], s[28:29], 0, v[158:159]
	s_add_i32 m0, s27, 0xe000
	s_nop 0
	global_load_lds_dwordx4 v[168:169], off
	s_waitcnt vmcnt(8)
	s_waitcnt lgkmcnt(0)
	s_barrier
	s_waitcnt lgkmcnt(0)
	v_mfma_f32_16x16x32_bf16 v[140:143], v[52:55], v[188:191], v[140:143]
	v_mfma_f32_16x16x32_bf16 v[136:139], v[64:67], v[188:191], v[136:139]
	v_mfma_f32_16x16x32_bf16 v[124:127], v[52:55], v[198:201], v[124:127]
	v_mfma_f32_16x16x32_bf16 v[120:123], v[64:67], v[198:201], v[120:123]
	v_mfma_f32_16x16x32_bf16 v[108:111], v[52:55], v[206:209], v[108:111]
	v_mfma_f32_16x16x32_bf16 v[104:107], v[64:67], v[206:209], v[104:107]
	v_mfma_f32_16x16x32_bf16 v[92:95], v[52:55], v[214:217], v[92:95]
	v_mfma_f32_16x16x32_bf16 v[88:91], v[64:67], v[214:217], v[88:91]
	v_mfma_f32_16x16x32_bf16 v[140:143], v[60:63], v[194:197], v[140:143]
	v_mfma_f32_16x16x32_bf16 v[136:139], v[72:75], v[194:197], v[136:139]
	v_mfma_f32_16x16x32_bf16 v[124:127], v[60:63], v[202:205], v[124:127]
	v_mfma_f32_16x16x32_bf16 v[120:123], v[72:75], v[202:205], v[120:123]
	v_mfma_f32_16x16x32_bf16 v[108:111], v[60:63], v[210:213], v[108:111]
	v_mfma_f32_16x16x32_bf16 v[104:107], v[72:75], v[210:213], v[104:107]
	v_mfma_f32_16x16x32_bf16 v[92:95], v[60:63], v[218:221], v[92:95]
	v_mfma_f32_16x16x32_bf16 v[88:91], v[72:75], v[218:221], v[88:91]
	v_mfma_f32_16x16x32_bf16 v[132:135], v[164:167], v[188:191], v[132:135]
	v_mfma_f32_16x16x32_bf16 v[128:131], v[180:183], v[188:191], v[128:131]
	v_mfma_f32_16x16x32_bf16 v[116:119], v[164:167], v[198:201], v[116:119]
	v_mfma_f32_16x16x32_bf16 v[112:115], v[180:183], v[198:201], v[112:115]
	v_mfma_f32_16x16x32_bf16 v[100:103], v[164:167], v[206:209], v[100:103]
	v_mfma_f32_16x16x32_bf16 v[96:99], v[180:183], v[206:209], v[96:99]
	v_mfma_f32_16x16x32_bf16 v[84:87], v[164:167], v[214:217], v[84:87]
	v_mfma_f32_16x16x32_bf16 v[80:83], v[180:183], v[214:217], v[80:83]
	v_mfma_f32_16x16x32_bf16 v[132:135], v[176:179], v[194:197], v[132:135]
	v_mfma_f32_16x16x32_bf16 v[128:131], v[184:187], v[194:197], v[128:131]
	v_mfma_f32_16x16x32_bf16 v[116:119], v[176:179], v[202:205], v[116:119]
	v_mfma_f32_16x16x32_bf16 v[112:115], v[184:187], v[202:205], v[112:115]
	v_mfma_f32_16x16x32_bf16 v[100:103], v[176:179], v[210:213], v[100:103]
	v_mfma_f32_16x16x32_bf16 v[96:99], v[184:187], v[210:213], v[96:99]
	v_mfma_f32_16x16x32_bf16 v[84:87], v[176:179], v[218:221], v[84:87]
	v_mfma_f32_16x16x32_bf16 v[80:83], v[184:187], v[218:221], v[80:83]
	s_barrier
	s_add_i32 s76, s69, s38
	v_lshl_add_u64 v[168:169], s[30:31], 0, v[150:151]
	s_mov_b32 m0, s76
	ds_read_b128 v[188:191], v173 offset:16384
	ds_read_b128 v[194:197], v173 offset:17408
	ds_read_b128 v[198:201], v173 offset:18432
	ds_read_b128 v[202:205], v173 offset:19456
	ds_read_b128 v[206:209], v173 offset:20480
	ds_read_b128 v[210:213], v173 offset:21504
	ds_read_b128 v[214:217], v173 offset:22528
	ds_read_b128 v[218:221], v173 offset:23552
	global_load_lds_dwordx4 v[168:169], off
	s_add_i32 m0, s76, 0x2000
	s_add_u32 s76, s30, 0x80000
	v_lshl_add_u64 v[222:223], s[30:31], 0, v[154:155]
	s_addc_u32 s77, s31, 0
	s_add_i32 s84, s70, s38
	global_load_lds_dwordx4 v[222:223], off
	v_lshl_add_u64 v[224:225], s[76:77], 0, v[150:151]
	s_mov_b32 m0, s84
	v_lshl_add_u64 v[226:227], s[34:35], 0, v[152:153]
	global_load_lds_dwordx4 v[224:225], off
	v_lshl_add_u64 v[224:225], s[76:77], 0, v[154:155]
	s_add_i32 m0, s84, 0x2000
	s_nop 0
	global_load_lds_dwordx4 v[224:225], off
	v_lshl_add_u64 v[224:225], s[34:35], 0, v[148:149]
	s_mov_b32 m0, s27
	s_nop 0
	global_load_lds_dwordx4 v[224:225], off
	s_mov_b32 m0, s39
	s_nop 0
	global_load_lds_dwordx4 v[226:227], off
	s_waitcnt vmcnt(8)
	s_waitcnt lgkmcnt(0)
	s_barrier
	s_waitcnt lgkmcnt(0)
	v_mfma_f32_16x16x32_bf16 v[76:79], v[52:55], v[188:191], v[76:79]
	v_mfma_f32_16x16x32_bf16 v[68:71], v[64:67], v[188:191], v[68:71]
	v_mfma_f32_16x16x32_bf16 v[44:47], v[52:55], v[198:201], v[44:47]
	v_mfma_f32_16x16x32_bf16 v[40:43], v[64:67], v[198:201], v[40:43]
	v_mfma_f32_16x16x32_bf16 v[28:31], v[52:55], v[206:209], v[28:31]
	v_mfma_f32_16x16x32_bf16 v[24:27], v[64:67], v[206:209], v[24:27]
	v_mfma_f32_16x16x32_bf16 v[12:15], v[52:55], v[214:217], v[12:15]
	v_mfma_f32_16x16x32_bf16 v[8:11], v[64:67], v[214:217], v[8:11]
	v_mfma_f32_16x16x32_bf16 v[76:79], v[60:63], v[194:197], v[76:79]
	v_mfma_f32_16x16x32_bf16 v[68:71], v[72:75], v[194:197], v[68:71]
	v_mfma_f32_16x16x32_bf16 v[44:47], v[60:63], v[202:205], v[44:47]
	v_mfma_f32_16x16x32_bf16 v[40:43], v[72:75], v[202:205], v[40:43]
	v_mfma_f32_16x16x32_bf16 v[28:31], v[60:63], v[210:213], v[28:31]
	v_mfma_f32_16x16x32_bf16 v[24:27], v[72:75], v[210:213], v[24:27]
	v_mfma_f32_16x16x32_bf16 v[12:15], v[60:63], v[218:221], v[12:15]
	v_mfma_f32_16x16x32_bf16 v[8:11], v[72:75], v[218:221], v[8:11]
	v_mfma_f32_16x16x32_bf16 v[48:51], v[180:183], v[188:191], v[48:51]
	v_mfma_f32_16x16x32_bf16 v[36:39], v[164:167], v[198:201], v[36:39]
	v_mfma_f32_16x16x32_bf16 v[32:35], v[180:183], v[198:201], v[32:35]
	v_mfma_f32_16x16x32_bf16 v[20:23], v[164:167], v[206:209], v[20:23]
	v_mfma_f32_16x16x32_bf16 v[16:19], v[180:183], v[206:209], v[16:19]
	v_mfma_f32_16x16x32_bf16 v[4:7], v[164:167], v[214:217], v[4:7]
	v_mfma_f32_16x16x32_bf16 v[0:3], v[180:183], v[214:217], v[0:3]
	v_mfma_f32_16x16x32_bf16 v[52:55], v[164:167], v[188:191], v[56:59]
	v_mfma_f32_16x16x32_bf16 v[48:51], v[184:187], v[194:197], v[48:51]
	v_mfma_f32_16x16x32_bf16 v[36:39], v[176:179], v[202:205], v[36:39]
	v_mfma_f32_16x16x32_bf16 v[32:35], v[184:187], v[202:205], v[32:35]
	v_mfma_f32_16x16x32_bf16 v[20:23], v[176:179], v[210:213], v[20:23]
	v_mfma_f32_16x16x32_bf16 v[16:19], v[184:187], v[210:213], v[16:19]
	v_mfma_f32_16x16x32_bf16 v[4:7], v[176:179], v[218:221], v[4:7]
	v_mfma_f32_16x16x32_bf16 v[0:3], v[184:187], v[218:221], v[0:3]
	v_mfma_f32_16x16x32_bf16 v[52:55], v[176:179], v[194:197], v[52:55]
	s_barrier
	s_add_i32 s76, 0, 0x18000
	s_add_i32 s77, 0, 0x1c000
	v_add_u32_e32 v72, s76, v170
	v_add_u32_e32 v175, s77, v170
	ds_read_b128 v[56:59], v72
	ds_read_b128 v[60:63], v72 offset:1024
	ds_read_b128 v[64:67], v72 offset:2048
	ds_read_b128 v[72:75], v72 offset:3072
	ds_read_b128 v[164:167], v175
	ds_read_b128 v[176:179], v175 offset:1024
	ds_read_b128 v[180:183], v175 offset:2048
	ds_read_b128 v[184:187], v175 offset:3072
	s_add_u32 s34, s34, 0x80000
	s_addc_u32 s35, s35, 0
	s_mov_b32 m0, s40
	v_lshl_add_u64 v[228:229], s[34:35], 0, v[148:149]
	ds_read_b128 v[188:191], v173 offset:32768
	ds_read_b128 v[194:197], v173 offset:33792
	ds_read_b128 v[198:201], v173 offset:34816
	ds_read_b128 v[202:205], v173 offset:35840
	ds_read_b128 v[206:209], v173 offset:36864
	ds_read_b128 v[210:213], v173 offset:37888
	ds_read_b128 v[214:217], v173 offset:38912
	ds_read_b128 v[218:221], v173 offset:39936
	global_load_lds_dwordx4 v[228:229], off
	v_lshl_add_u64 v[228:229], s[34:35], 0, v[152:153]
	s_mov_b32 m0, s41
	s_nop 0
	global_load_lds_dwordx4 v[228:229], off
	s_waitcnt vmcnt(8)
	s_waitcnt lgkmcnt(0)
	s_barrier
	s_waitcnt lgkmcnt(0)
	v_mfma_f32_16x16x32_bf16 v[140:143], v[56:59], v[188:191], v[140:143]
	v_mfma_f32_16x16x32_bf16 v[136:139], v[64:67], v[188:191], v[136:139]
	v_mfma_f32_16x16x32_bf16 v[124:127], v[56:59], v[198:201], v[124:127]
	v_mfma_f32_16x16x32_bf16 v[120:123], v[64:67], v[198:201], v[120:123]
	v_mfma_f32_16x16x32_bf16 v[108:111], v[56:59], v[206:209], v[108:111]
	v_mfma_f32_16x16x32_bf16 v[104:107], v[64:67], v[206:209], v[104:107]
	v_mfma_f32_16x16x32_bf16 v[92:95], v[56:59], v[214:217], v[92:95]
	v_mfma_f32_16x16x32_bf16 v[88:91], v[64:67], v[214:217], v[88:91]
	v_mfma_f32_16x16x32_bf16 v[140:143], v[60:63], v[194:197], v[140:143]
	v_mfma_f32_16x16x32_bf16 v[136:139], v[72:75], v[194:197], v[136:139]
	v_mfma_f32_16x16x32_bf16 v[124:127], v[60:63], v[202:205], v[124:127]
	v_mfma_f32_16x16x32_bf16 v[120:123], v[72:75], v[202:205], v[120:123]
	v_mfma_f32_16x16x32_bf16 v[108:111], v[60:63], v[210:213], v[108:111]
	v_mfma_f32_16x16x32_bf16 v[104:107], v[72:75], v[210:213], v[104:107]
	v_mfma_f32_16x16x32_bf16 v[92:95], v[60:63], v[218:221], v[92:95]
	v_mfma_f32_16x16x32_bf16 v[88:91], v[72:75], v[218:221], v[88:91]
	v_mfma_f32_16x16x32_bf16 v[132:135], v[164:167], v[188:191], v[132:135]
	v_mfma_f32_16x16x32_bf16 v[128:131], v[180:183], v[188:191], v[128:131]
	v_mfma_f32_16x16x32_bf16 v[116:119], v[164:167], v[198:201], v[116:119]
	v_mfma_f32_16x16x32_bf16 v[112:115], v[180:183], v[198:201], v[112:115]
	v_mfma_f32_16x16x32_bf16 v[100:103], v[164:167], v[206:209], v[100:103]
	v_mfma_f32_16x16x32_bf16 v[96:99], v[180:183], v[206:209], v[96:99]
	v_mfma_f32_16x16x32_bf16 v[84:87], v[164:167], v[214:217], v[84:87]
	v_mfma_f32_16x16x32_bf16 v[80:83], v[180:183], v[214:217], v[80:83]
	v_mfma_f32_16x16x32_bf16 v[132:135], v[176:179], v[194:197], v[132:135]
	v_mfma_f32_16x16x32_bf16 v[128:131], v[184:187], v[194:197], v[128:131]
	v_mfma_f32_16x16x32_bf16 v[116:119], v[176:179], v[202:205], v[116:119]
	v_mfma_f32_16x16x32_bf16 v[112:115], v[184:187], v[202:205], v[112:115]
	v_mfma_f32_16x16x32_bf16 v[100:103], v[176:179], v[210:213], v[100:103]
	v_mfma_f32_16x16x32_bf16 v[96:99], v[184:187], v[210:213], v[96:99]
	v_mfma_f32_16x16x32_bf16 v[84:87], v[176:179], v[218:221], v[84:87]
	v_mfma_f32_16x16x32_bf16 v[80:83], v[184:187], v[218:221], v[80:83]
	s_barrier
	s_add_i32 s34, s76, s38
	v_lshl_add_u64 v[168:169], v[168:169], 0, s[14:15]
	s_mov_b32 m0, s34
	ds_read_b128 v[188:191], v173 offset:49152
	ds_read_b128 v[194:197], v173 offset:50176
	ds_read_b128 v[198:201], v173 offset:51200
	ds_read_b128 v[202:205], v173 offset:52224
	ds_read_b128 v[206:209], v173 offset:53248
	ds_read_b128 v[210:213], v173 offset:54272
	ds_read_b128 v[214:217], v173 offset:55296
	ds_read_b128 v[218:221], v173 offset:56320
	global_load_lds_dwordx4 v[168:169], off
	s_add_i32 m0, s34, 0x2000
	s_add_u32 s30, s30, 0x80080
	v_lshl_add_u64 v[168:169], v[222:223], 0, s[14:15]
	s_addc_u32 s31, s31, 0
	s_add_i32 s34, s77, s38
	global_load_lds_dwordx4 v[168:169], off
	v_lshl_add_u64 v[168:169], s[30:31], 0, v[150:151]
	s_mov_b32 m0, s34
	s_nop 0
	global_load_lds_dwordx4 v[168:169], off
	v_lshl_add_u64 v[168:169], s[30:31], 0, v[154:155]
	s_add_i32 m0, s34, 0x2000
	s_nop 0
	global_load_lds_dwordx4 v[168:169], off
	v_lshl_add_u64 v[168:169], v[224:225], 0, s[14:15]
	s_mov_b32 m0, s57
	s_nop 0
	global_load_lds_dwordx4 v[168:169], off
	v_lshl_add_u64 v[168:169], v[226:227], 0, s[14:15]
	s_mov_b32 m0, s66
	s_nop 0
	global_load_lds_dwordx4 v[168:169], off
	s_waitcnt vmcnt(8)
	s_waitcnt lgkmcnt(0)
	s_barrier
	s_waitcnt lgkmcnt(0)
	v_mfma_f32_16x16x32_bf16 v[76:79], v[56:59], v[188:191], v[76:79]
	v_mfma_f32_16x16x32_bf16 v[68:71], v[64:67], v[188:191], v[68:71]
	v_mfma_f32_16x16x32_bf16 v[44:47], v[56:59], v[198:201], v[44:47]
	v_mfma_f32_16x16x32_bf16 v[40:43], v[64:67], v[198:201], v[40:43]
	v_mfma_f32_16x16x32_bf16 v[28:31], v[56:59], v[206:209], v[28:31]
	v_mfma_f32_16x16x32_bf16 v[24:27], v[64:67], v[206:209], v[24:27]
	v_mfma_f32_16x16x32_bf16 v[12:15], v[56:59], v[214:217], v[12:15]
	v_mfma_f32_16x16x32_bf16 v[8:11], v[64:67], v[214:217], v[8:11]
	v_mfma_f32_16x16x32_bf16 v[76:79], v[60:63], v[194:197], v[76:79]
	v_mfma_f32_16x16x32_bf16 v[68:71], v[72:75], v[194:197], v[68:71]
	v_mfma_f32_16x16x32_bf16 v[44:47], v[60:63], v[202:205], v[44:47]
	v_mfma_f32_16x16x32_bf16 v[40:43], v[72:75], v[202:205], v[40:43]
	v_mfma_f32_16x16x32_bf16 v[28:31], v[60:63], v[210:213], v[28:31]
	v_mfma_f32_16x16x32_bf16 v[24:27], v[72:75], v[210:213], v[24:27]
	v_mfma_f32_16x16x32_bf16 v[12:15], v[60:63], v[218:221], v[12:15]
	v_mfma_f32_16x16x32_bf16 v[8:11], v[72:75], v[218:221], v[8:11]
	v_mfma_f32_16x16x32_bf16 v[52:55], v[164:167], v[188:191], v[52:55]
	v_mfma_f32_16x16x32_bf16 v[48:51], v[180:183], v[188:191], v[48:51]
	v_mfma_f32_16x16x32_bf16 v[36:39], v[164:167], v[198:201], v[36:39]
	v_mfma_f32_16x16x32_bf16 v[32:35], v[180:183], v[198:201], v[32:35]
	v_mfma_f32_16x16x32_bf16 v[20:23], v[164:167], v[206:209], v[20:23]
	v_mfma_f32_16x16x32_bf16 v[16:19], v[180:183], v[206:209], v[16:19]
	v_mfma_f32_16x16x32_bf16 v[4:7], v[164:167], v[214:217], v[4:7]
	v_mfma_f32_16x16x32_bf16 v[0:3], v[180:183], v[214:217], v[0:3]
	v_mfma_f32_16x16x32_bf16 v[56:59], v[176:179], v[194:197], v[52:55]
	v_mfma_f32_16x16x32_bf16 v[48:51], v[184:187], v[194:197], v[48:51]
	v_mfma_f32_16x16x32_bf16 v[36:39], v[176:179], v[202:205], v[36:39]
	v_mfma_f32_16x16x32_bf16 v[32:35], v[184:187], v[202:205], v[32:35]
	v_mfma_f32_16x16x32_bf16 v[20:23], v[176:179], v[210:213], v[20:23]
	v_mfma_f32_16x16x32_bf16 v[16:19], v[184:187], v[210:213], v[16:19]
	v_mfma_f32_16x16x32_bf16 v[4:7], v[176:179], v[218:221], v[4:7]
	v_mfma_f32_16x16x32_bf16 v[0:3], v[184:187], v[218:221], v[0:3]
	s_barrier
	s_add_i32 s75, s75, 2
	s_add_u32 s28, s28, 0x100
	s_addc_u32 s29, s29, 0
	s_add_u32 s73, s73, 0x100
	s_addc_u32 s74, s74, 0
	s_cmp_gt_u32 s75, 29
	s_cbranch_scc0 .LBB0_202
	s_and_b64 vcc, exec, s[16:17]
	s_cbranch_vccz .LBB0_205
	s_barrier

.LBB0_240:
	s_setprio 0
	s_waitcnt vmcnt(0)
	s_barrier
	s_cmp_lt_u32 s81, 4
	s_cbranch_scc1 .LBB0_294

.LBB0_522:
	s_cmp_ge_u32 s3, 4
	s_cbranch_scc0 .Lprio_skip1
	s_setprio 1
.Lprio_skip1:
	s_cmp_lt_i32 s80, 7
	s_cselect_b64 s[0:1], -1, 0
	s_cmp_gt_i32 s81, 6
	s_cselect_b64 s[4:5], -1, 0
	s_and_b64 s[0:1], s[0:1], s[4:5]
	s_andn2_b64 vcc, exec, s[0:1]
	s_cbranch_vccnz .LBB0_622
	v_lshrrev_b32_e32 v2, 1, v144
	v_lshrrev_b32_e32 v3, 5, v144
	v_and_b32_e32 v2, 24, v2
	v_and_b32_e32 v3, 4, v3
	v_bfe_u32 v4, v144, 2, 2
	v_lshlrev_b32_e32 v0, 4, v144
	v_and_b32_e32 v1, 32, v144
	v_bfe_u32 v10, v144, 2, 4
	v_or3_b32 v2, v3, v4, v2
	v_lshrrev_b32_e32 v3, 3, v144
	s_movk_i32 s0, 0x70
	v_bitop3_b32 v8, v0, v1, 48 bitop3:0x6c
	v_and_b32_e32 v9, 64, v144
	v_and_or_b32 v4, v3, s0, v10
	s_movk_i32 s0, 0x60
	v_add_u32_e32 v11, 0x2000, v0
	v_or_b32_e32 v1, v8, v9
	v_and_or_b32 v3, v3, s0, v2
	v_lshrrev_b32_e32 v0, 7, v11
	s_movk_i32 s0, 0xf0
	s_add_u32 s30, s62, 0x4000000
	v_lshl_or_b32 v150, v4, 12, v1
	v_and_or_b32 v3, v0, s0, v10
	s_movk_i32 s0, 0xe0
	s_addc_u32 s31, s63, 0
	v_and_or_b32 v0, v0, s0, v2
	s_lshl_b32 s0, s2, 2
	s_and_b32 s0, s0, 28
	s_ashr_i32 s1, s2, 6
	s_add_i32 s0, s0, s1
	s_waitcnt lgkmcnt(0)
	s_bfe_u32 s16, s2, 0x30003
	s_ashr_i32 s1, s0, 31
	s_lshl_b64 s[6:7], s[0:1], 20
	s_lshl_b32 s2, s16, 20
	s_add_u32 s1, s62, s2
	s_addc_u32 s3, s63, 0
	s_add_u32 s4, s1, 0x1200000
	s_addc_u32 s5, s3, 0
	s_add_u32 s8, s1, 0x1280000
	s_addc_u32 s9, s3, 0
	s_add_u32 s6, s30, s6
	s_addc_u32 s7, s31, s7
	s_add_u32 s10, s6, 0x80000
	v_readfirstlane_b32 s3, v144
	s_addc_u32 s11, s7, 0
	s_lshr_b32 s18, s3, 6
	s_lshl_b32 s1, s18, 10
	s_add_i32 s34, s1, 0
	s_add_i32 m0, s34, 0x10000
	v_lshl_or_b32 v154, v3, 12, v1
	global_load_lds_dwordx4 v150, s[4:5]
	s_add_i32 m0, s34, 0x12000
	v_lshl_or_b32 v148, v4, 12, v1
	global_load_lds_dwordx4 v154, s[4:5]
	s_add_i32 m0, s34, 0x14000
	s_add_i32 s35, s34, 0x2000
	global_load_lds_dwordx4 v150, s[8:9]
	s_add_i32 m0, s34, 0x16000
	v_lshl_or_b32 v152, v3, 12, v1
	global_load_lds_dwordx4 v154, s[8:9]
	s_mov_b32 m0, s34
	s_add_i32 s36, s34, 0x4000
	global_load_lds_dwordx4 v148, s[6:7]
	s_mov_b32 m0, s35
	s_add_i32 s37, s34, 0x6000
	global_load_lds_dwordx4 v152, s[6:7]
	s_mov_b32 m0, s36
	v_mov_b32_e32 v151, 0
	global_load_lds_dwordx4 v148, s[10:11]
	s_mov_b32 m0, s37
	s_lshr_b32 s19, s3, 8
	global_load_lds_dwordx4 v152, s[10:11]
	v_mov_b32_e32 v155, v151
	v_mov_b32_e32 v149, v151
	v_mov_b32_e32 v153, v151
	s_cmp_eq_u32 s19, 1
	s_mov_b32 s38, 0
	v_lshl_add_u64 v[0:1], s[4:5], 0, v[150:151]
	v_lshl_add_u64 v[2:3], s[4:5], 0, v[154:155]
	v_lshl_add_u64 v[4:5], s[6:7], 0, v[148:149]
	s_cselect_b64 s[8:9], -1, 0
	s_cmp_lg_u32 s19, 1
	v_lshl_add_u64 v[6:7], s[6:7], 0, v[152:153]
	s_cbranch_scc1 .LBB0_525
	s_barrier

.LBB0_529:
	ds_read_b128 v[96:99], v179
	ds_read_b128 v[100:103], v179 offset:1024
	ds_read_b128 v[104:107], v179 offset:2048
	ds_read_b128 v[108:111], v179 offset:3072
	ds_read_b128 v[156:159], v180
	ds_read_b128 v[160:163], v180 offset:1024
	ds_read_b128 v[164:167], v180 offset:2048
	ds_read_b128 v[168:171], v180 offset:3072
	s_add_u32 s26, s2, 0xfff80080
	s_addc_u32 s27, s3, -1
	s_cmp_eq_u32 s70, 28
	s_cselect_b32 s29, s68, s27
	s_cselect_b32 s28, s69, s26
	s_cselect_b32 s27, s5, s25
	s_cselect_b32 s26, s4, s24
	v_lshl_add_u64 v[214:215], s[2:3], 0, v[144:145]
	s_add_i32 m0, s34, 0xc000
	ds_read_b128 v[172:175], v181
	ds_read_b128 v[184:187], v181 offset:1024
	ds_read_b128 v[188:191], v181 offset:2048
	ds_read_b128 v[194:197], v181 offset:3072
	ds_read_b128 v[198:201], v181 offset:4096
	ds_read_b128 v[202:205], v181 offset:5120
	ds_read_b128 v[206:209], v181 offset:6144
	ds_read_b128 v[210:213], v181 offset:7168
	global_load_lds_dwordx4 v[214:215], off
	v_lshl_add_u64 v[214:215], s[2:3], 0, v[146:147]
	s_add_i32 m0, s34, 0xe000
	s_nop 0
	global_load_lds_dwordx4 v[214:215], off
	s_waitcnt vmcnt(8)
	s_waitcnt lgkmcnt(0)
	s_barrier
	s_waitcnt lgkmcnt(0)
	v_mfma_f32_16x16x32_bf16 v[140:143], v[96:99], v[172:175], v[140:143]
	v_mfma_f32_16x16x32_bf16 v[136:139], v[104:107], v[172:175], v[136:139]
	v_mfma_f32_16x16x32_bf16 v[124:127], v[96:99], v[188:191], v[124:127]
	v_mfma_f32_16x16x32_bf16 v[120:123], v[104:107], v[188:191], v[120:123]
	v_mfma_f32_16x16x32_bf16 v[92:95], v[96:99], v[198:201], v[92:95]
	v_mfma_f32_16x16x32_bf16 v[88:91], v[104:107], v[198:201], v[88:91]
	v_mfma_f32_16x16x32_bf16 v[76:79], v[96:99], v[206:209], v[76:79]
	v_mfma_f32_16x16x32_bf16 v[72:75], v[104:107], v[206:209], v[72:75]
	v_mfma_f32_16x16x32_bf16 v[140:143], v[100:103], v[184:187], v[140:143]
	v_mfma_f32_16x16x32_bf16 v[136:139], v[108:111], v[184:187], v[136:139]
	v_mfma_f32_16x16x32_bf16 v[124:127], v[100:103], v[194:197], v[124:127]
	v_mfma_f32_16x16x32_bf16 v[120:123], v[108:111], v[194:197], v[120:123]
	v_mfma_f32_16x16x32_bf16 v[92:95], v[100:103], v[202:205], v[92:95]
	v_mfma_f32_16x16x32_bf16 v[88:91], v[108:111], v[202:205], v[88:91]
	v_mfma_f32_16x16x32_bf16 v[76:79], v[100:103], v[210:213], v[76:79]
	v_mfma_f32_16x16x32_bf16 v[72:75], v[108:111], v[210:213], v[72:75]
	v_mfma_f32_16x16x32_bf16 v[132:135], v[156:159], v[172:175], v[132:135]
	v_mfma_f32_16x16x32_bf16 v[128:131], v[164:167], v[172:175], v[128:131]
	v_mfma_f32_16x16x32_bf16 v[116:119], v[156:159], v[188:191], v[116:119]
	v_mfma_f32_16x16x32_bf16 v[112:115], v[164:167], v[188:191], v[112:115]
	v_mfma_f32_16x16x32_bf16 v[84:87], v[156:159], v[198:201], v[84:87]
	v_mfma_f32_16x16x32_bf16 v[80:83], v[164:167], v[198:201], v[80:83]
	v_mfma_f32_16x16x32_bf16 v[68:71], v[156:159], v[206:209], v[68:71]
	v_mfma_f32_16x16x32_bf16 v[64:67], v[164:167], v[206:209], v[64:67]
	v_mfma_f32_16x16x32_bf16 v[132:135], v[160:163], v[184:187], v[132:135]
	v_mfma_f32_16x16x32_bf16 v[128:131], v[168:171], v[184:187], v[128:131]
	v_mfma_f32_16x16x32_bf16 v[116:119], v[160:163], v[194:197], v[116:119]
	v_mfma_f32_16x16x32_bf16 v[112:115], v[168:171], v[194:197], v[112:115]
	v_mfma_f32_16x16x32_bf16 v[84:87], v[160:163], v[202:205], v[84:87]
	v_mfma_f32_16x16x32_bf16 v[80:83], v[168:171], v[202:205], v[80:83]
	v_mfma_f32_16x16x32_bf16 v[68:71], v[160:163], v[210:213], v[68:71]
	v_mfma_f32_16x16x32_bf16 v[64:67], v[168:171], v[210:213], v[64:67]
	s_barrier
	s_add_i32 s71, s54, s1
	v_lshl_add_u64 v[214:215], s[26:27], 0, v[150:151]
	s_mov_b32 m0, s71
	ds_read_b128 v[172:175], v181 offset:16384
	ds_read_b128 v[184:187], v181 offset:17408
	ds_read_b128 v[188:191], v181 offset:18432
	ds_read_b128 v[194:197], v181 offset:19456
	ds_read_b128 v[198:201], v181 offset:20480
	ds_read_b128 v[202:205], v181 offset:21504
	ds_read_b128 v[206:209], v181 offset:22528
	ds_read_b128 v[210:213], v181 offset:23552
	global_load_lds_dwordx4 v[214:215], off
	s_add_i32 m0, s71, 0x2000
	s_add_u32 s72, s26, 0x80000
	v_lshl_add_u64 v[216:217], s[26:27], 0, v[154:155]
	s_addc_u32 s73, s27, 0
	s_add_i32 s71, s55, s1
	global_load_lds_dwordx4 v[216:217], off
	v_lshl_add_u64 v[218:219], s[72:73], 0, v[150:151]
	s_mov_b32 m0, s71
	v_lshl_add_u64 v[220:221], s[28:29], 0, v[152:153]
	global_load_lds_dwordx4 v[218:219], off
	v_lshl_add_u64 v[218:219], s[72:73], 0, v[154:155]
	s_add_i32 m0, s71, 0x2000
	s_nop 0
	global_load_lds_dwordx4 v[218:219], off
	v_lshl_add_u64 v[218:219], s[28:29], 0, v[148:149]
	s_mov_b32 m0, s34
	s_nop 0
	global_load_lds_dwordx4 v[218:219], off
	s_mov_b32 m0, s35
	s_nop 0
	global_load_lds_dwordx4 v[220:221], off
	s_waitcnt vmcnt(8)
	s_waitcnt lgkmcnt(0)
	s_barrier
	s_waitcnt lgkmcnt(0)
	v_mfma_f32_16x16x32_bf16 v[60:63], v[96:99], v[172:175], v[60:63]
	v_mfma_f32_16x16x32_bf16 v[56:59], v[104:107], v[172:175], v[56:59]
	v_mfma_f32_16x16x32_bf16 v[44:47], v[96:99], v[188:191], v[44:47]
	v_mfma_f32_16x16x32_bf16 v[40:43], v[104:107], v[188:191], v[40:43]
	v_mfma_f32_16x16x32_bf16 v[28:31], v[96:99], v[198:201], v[28:31]
	v_mfma_f32_16x16x32_bf16 v[24:27], v[104:107], v[198:201], v[24:27]
	v_mfma_f32_16x16x32_bf16 v[12:15], v[96:99], v[206:209], v[12:15]
	v_mfma_f32_16x16x32_bf16 v[8:11], v[104:107], v[206:209], v[8:11]
	v_mfma_f32_16x16x32_bf16 v[60:63], v[100:103], v[184:187], v[60:63]
	v_mfma_f32_16x16x32_bf16 v[56:59], v[108:111], v[184:187], v[56:59]
	v_mfma_f32_16x16x32_bf16 v[44:47], v[100:103], v[194:197], v[44:47]
	v_mfma_f32_16x16x32_bf16 v[40:43], v[108:111], v[194:197], v[40:43]
	v_mfma_f32_16x16x32_bf16 v[28:31], v[100:103], v[202:205], v[28:31]
	v_mfma_f32_16x16x32_bf16 v[24:27], v[108:111], v[202:205], v[24:27]
	v_mfma_f32_16x16x32_bf16 v[12:15], v[100:103], v[210:213], v[12:15]
	v_mfma_f32_16x16x32_bf16 v[8:11], v[108:111], v[210:213], v[8:11]
	v_mfma_f32_16x16x32_bf16 v[52:55], v[156:159], v[172:175], v[52:55]
	v_mfma_f32_16x16x32_bf16 v[48:51], v[164:167], v[172:175], v[48:51]
	v_mfma_f32_16x16x32_bf16 v[36:39], v[156:159], v[188:191], v[36:39]
	v_mfma_f32_16x16x32_bf16 v[32:35], v[164:167], v[188:191], v[32:35]
	v_mfma_f32_16x16x32_bf16 v[20:23], v[156:159], v[198:201], v[20:23]
	v_mfma_f32_16x16x32_bf16 v[16:19], v[164:167], v[198:201], v[16:19]
	v_mfma_f32_16x16x32_bf16 v[4:7], v[156:159], v[206:209], v[4:7]
	v_mfma_f32_16x16x32_bf16 v[0:3], v[164:167], v[206:209], v[0:3]
	v_mfma_f32_16x16x32_bf16 v[52:55], v[160:163], v[184:187], v[52:55]
	v_mfma_f32_16x16x32_bf16 v[48:51], v[168:171], v[184:187], v[48:51]
	v_mfma_f32_16x16x32_bf16 v[36:39], v[160:163], v[194:197], v[36:39]
	v_mfma_f32_16x16x32_bf16 v[32:35], v[168:171], v[194:197], v[32:35]
	v_mfma_f32_16x16x32_bf16 v[20:23], v[160:163], v[202:205], v[20:23]
	v_mfma_f32_16x16x32_bf16 v[16:19], v[168:171], v[202:205], v[16:19]
	v_mfma_f32_16x16x32_bf16 v[4:7], v[160:163], v[210:213], v[4:7]
	v_mfma_f32_16x16x32_bf16 v[0:3], v[168:171], v[210:213], v[0:3]
	s_barrier
	s_add_i32 s71, 0, 0x18000
	s_add_i32 s72, 0, 0x1c000
	v_add_u32_e32 v108, s71, v178
	v_add_u32_e32 v168, s72, v178
	ds_read_b128 v[96:99], v108
	ds_read_b128 v[100:103], v108 offset:1024
	ds_read_b128 v[104:107], v108 offset:2048
	ds_read_b128 v[108:111], v108 offset:3072
	ds_read_b128 v[156:159], v168
	ds_read_b128 v[160:163], v168 offset:1024
	ds_read_b128 v[164:167], v168 offset:2048
	ds_read_b128 v[168:171], v168 offset:3072
	s_add_u32 s28, s28, 0x80000
	s_addc_u32 s29, s29, 0
	s_mov_b32 m0, s36
	v_lshl_add_u64 v[222:223], s[28:29], 0, v[148:149]
	ds_read_b128 v[172:175], v181 offset:32768
	ds_read_b128 v[184:187], v181 offset:33792
	ds_read_b128 v[188:191], v181 offset:34816
	ds_read_b128 v[194:197], v181 offset:35840
	ds_read_b128 v[198:201], v181 offset:36864
	ds_read_b128 v[202:205], v181 offset:37888
	ds_read_b128 v[206:209], v181 offset:38912
	ds_read_b128 v[210:213], v181 offset:39936
	global_load_lds_dwordx4 v[222:223], off
	v_lshl_add_u64 v[222:223], s[28:29], 0, v[152:153]
	s_mov_b32 m0, s37
	s_nop 0
	global_load_lds_dwordx4 v[222:223], off
	s_waitcnt vmcnt(8)
	s_waitcnt lgkmcnt(0)
	s_barrier
	s_waitcnt lgkmcnt(0)
	v_mfma_f32_16x16x32_bf16 v[140:143], v[96:99], v[172:175], v[140:143]
	v_mfma_f32_16x16x32_bf16 v[136:139], v[104:107], v[172:175], v[136:139]
	v_mfma_f32_16x16x32_bf16 v[124:127], v[96:99], v[188:191], v[124:127]
	v_mfma_f32_16x16x32_bf16 v[120:123], v[104:107], v[188:191], v[120:123]
	v_mfma_f32_16x16x32_bf16 v[92:95], v[96:99], v[198:201], v[92:95]
	v_mfma_f32_16x16x32_bf16 v[88:91], v[104:107], v[198:201], v[88:91]
	v_mfma_f32_16x16x32_bf16 v[76:79], v[96:99], v[206:209], v[76:79]
	v_mfma_f32_16x16x32_bf16 v[72:75], v[104:107], v[206:209], v[72:75]
	v_mfma_f32_16x16x32_bf16 v[140:143], v[100:103], v[184:187], v[140:143]
	v_mfma_f32_16x16x32_bf16 v[136:139], v[108:111], v[184:187], v[136:139]
	v_mfma_f32_16x16x32_bf16 v[124:127], v[100:103], v[194:197], v[124:127]
	v_mfma_f32_16x16x32_bf16 v[120:123], v[108:111], v[194:197], v[120:123]
	v_mfma_f32_16x16x32_bf16 v[92:95], v[100:103], v[202:205], v[92:95]
	v_mfma_f32_16x16x32_bf16 v[88:91], v[108:111], v[202:205], v[88:91]
	v_mfma_f32_16x16x32_bf16 v[76:79], v[100:103], v[210:213], v[76:79]
	v_mfma_f32_16x16x32_bf16 v[72:75], v[108:111], v[210:213], v[72:75]
	v_mfma_f32_16x16x32_bf16 v[132:135], v[156:159], v[172:175], v[132:135]
	v_mfma_f32_16x16x32_bf16 v[128:131], v[164:167], v[172:175], v[128:131]
	v_mfma_f32_16x16x32_bf16 v[116:119], v[156:159], v[188:191], v[116:119]
	v_mfma_f32_16x16x32_bf16 v[112:115], v[164:167], v[188:191], v[112:115]
	v_mfma_f32_16x16x32_bf16 v[84:87], v[156:159], v[198:201], v[84:87]
	v_mfma_f32_16x16x32_bf16 v[80:83], v[164:167], v[198:201], v[80:83]
	v_mfma_f32_16x16x32_bf16 v[68:71], v[156:159], v[206:209], v[68:71]
	v_mfma_f32_16x16x32_bf16 v[64:67], v[164:167], v[206:209], v[64:67]
	v_mfma_f32_16x16x32_bf16 v[132:135], v[160:163], v[184:187], v[132:135]
	v_mfma_f32_16x16x32_bf16 v[128:131], v[168:171], v[184:187], v[128:131]
	v_mfma_f32_16x16x32_bf16 v[116:119], v[160:163], v[194:197], v[116:119]
	v_mfma_f32_16x16x32_bf16 v[112:115], v[168:171], v[194:197], v[112:115]
	v_mfma_f32_16x16x32_bf16 v[84:87], v[160:163], v[202:205], v[84:87]
	v_mfma_f32_16x16x32_bf16 v[80:83], v[168:171], v[202:205], v[80:83]
	v_mfma_f32_16x16x32_bf16 v[68:71], v[160:163], v[210:213], v[68:71]
	v_mfma_f32_16x16x32_bf16 v[64:67], v[168:171], v[210:213], v[64:67]
	s_barrier
	s_add_i32 s28, s71, s1
	v_lshl_add_u64 v[214:215], v[214:215], 0, s[14:15]
	s_mov_b32 m0, s28
	ds_read_b128 v[172:175], v181 offset:49152
	ds_read_b128 v[184:187], v181 offset:50176
	ds_read_b128 v[188:191], v181 offset:51200
	ds_read_b128 v[194:197], v181 offset:52224
	ds_read_b128 v[198:201], v181 offset:53248
	ds_read_b128 v[202:205], v181 offset:54272
	ds_read_b128 v[206:209], v181 offset:55296
	ds_read_b128 v[210:213], v181 offset:56320
	global_load_lds_dwordx4 v[214:215], off
	s_add_i32 m0, s28, 0x2000
	s_add_u32 s26, s26, 0x80080
	v_lshl_add_u64 v[214:215], v[216:217], 0, s[14:15]
	s_addc_u32 s27, s27, 0
	s_add_i32 s28, s72, s1
	global_load_lds_dwordx4 v[214:215], off
	v_lshl_add_u64 v[214:215], s[26:27], 0, v[150:151]
	s_mov_b32 m0, s28
	s_nop 0
	global_load_lds_dwordx4 v[214:215], off
	v_lshl_add_u64 v[214:215], s[26:27], 0, v[154:155]
	s_add_i32 m0, s28, 0x2000
	s_nop 0
	global_load_lds_dwordx4 v[214:215], off
	v_lshl_add_u64 v[214:215], v[218:219], 0, s[14:15]
	s_mov_b32 m0, s43
	s_nop 0
	global_load_lds_dwordx4 v[214:215], off
	v_lshl_add_u64 v[214:215], v[220:221], 0, s[14:15]
	s_mov_b32 m0, s48
	s_nop 0
	global_load_lds_dwordx4 v[214:215], off
	s_waitcnt vmcnt(8)
	s_waitcnt lgkmcnt(0)
	s_barrier
	s_waitcnt lgkmcnt(0)
	v_mfma_f32_16x16x32_bf16 v[60:63], v[96:99], v[172:175], v[60:63]
	v_mfma_f32_16x16x32_bf16 v[56:59], v[104:107], v[172:175], v[56:59]
	v_mfma_f32_16x16x32_bf16 v[44:47], v[96:99], v[188:191], v[44:47]
	v_mfma_f32_16x16x32_bf16 v[40:43], v[104:107], v[188:191], v[40:43]
	v_mfma_f32_16x16x32_bf16 v[28:31], v[96:99], v[198:201], v[28:31]
	v_mfma_f32_16x16x32_bf16 v[24:27], v[104:107], v[198:201], v[24:27]
	v_mfma_f32_16x16x32_bf16 v[12:15], v[96:99], v[206:209], v[12:15]
	v_mfma_f32_16x16x32_bf16 v[8:11], v[104:107], v[206:209], v[8:11]
	v_mfma_f32_16x16x32_bf16 v[60:63], v[100:103], v[184:187], v[60:63]
	v_mfma_f32_16x16x32_bf16 v[56:59], v[108:111], v[184:187], v[56:59]
	v_mfma_f32_16x16x32_bf16 v[44:47], v[100:103], v[194:197], v[44:47]
	v_mfma_f32_16x16x32_bf16 v[40:43], v[108:111], v[194:197], v[40:43]
	v_mfma_f32_16x16x32_bf16 v[28:31], v[100:103], v[202:205], v[28:31]
	v_mfma_f32_16x16x32_bf16 v[24:27], v[108:111], v[202:205], v[24:27]
	v_mfma_f32_16x16x32_bf16 v[12:15], v[100:103], v[210:213], v[12:15]
	v_mfma_f32_16x16x32_bf16 v[8:11], v[108:111], v[210:213], v[8:11]
	v_mfma_f32_16x16x32_bf16 v[52:55], v[156:159], v[172:175], v[52:55]
	v_mfma_f32_16x16x32_bf16 v[48:51], v[164:167], v[172:175], v[48:51]
	v_mfma_f32_16x16x32_bf16 v[36:39], v[156:159], v[188:191], v[36:39]
	v_mfma_f32_16x16x32_bf16 v[32:35], v[164:167], v[188:191], v[32:35]
	v_mfma_f32_16x16x32_bf16 v[20:23], v[156:159], v[198:201], v[20:23]
	v_mfma_f32_16x16x32_bf16 v[16:19], v[164:167], v[198:201], v[16:19]
	v_mfma_f32_16x16x32_bf16 v[4:7], v[156:159], v[206:209], v[4:7]
	v_mfma_f32_16x16x32_bf16 v[0:3], v[164:167], v[206:209], v[0:3]
	v_mfma_f32_16x16x32_bf16 v[52:55], v[160:163], v[184:187], v[52:55]
	v_mfma_f32_16x16x32_bf16 v[48:51], v[168:171], v[184:187], v[48:51]
	v_mfma_f32_16x16x32_bf16 v[36:39], v[160:163], v[194:197], v[36:39]
	v_mfma_f32_16x16x32_bf16 v[32:35], v[168:171], v[194:197], v[32:35]
	v_mfma_f32_16x16x32_bf16 v[20:23], v[160:163], v[202:205], v[20:23]
	v_mfma_f32_16x16x32_bf16 v[16:19], v[168:171], v[202:205], v[16:19]
	v_mfma_f32_16x16x32_bf16 v[4:7], v[160:163], v[210:213], v[4:7]
	v_mfma_f32_16x16x32_bf16 v[0:3], v[168:171], v[210:213], v[0:3]
	s_barrier
	s_add_i32 s70, s70, 2
	s_add_u32 s2, s2, 0x100
	s_addc_u32 s3, s3, 0
	s_add_u32 s24, s24, 0x100
	s_addc_u32 s25, s25, 0
	s_cmp_gt_u32 s70, 29
	s_cbranch_scc0 .LBB0_529
	s_and_b64 vcc, exec, s[18:19]
	s_cbranch_vccz .LBB0_532
	s_barrier

.LBB0_568:
	s_setprio 0
	s_waitcnt vmcnt(0)
	s_cmp_lt_u32 s81, 8
	s_barrier
	s_cbranch_scc1 .LBB0_622
	s_waitcnt vmcnt(0)
	s_barrier
	s_and_saveexec_b64 s[0:1], s[44:45]
	s_cbranch_execz .LBB0_621
	s_add_u32 s2, s62, 0x3300200
	s_addc_u32 s3, s63, 0
	s_add_i32 s4, 0, 0x23fc0
	v_mov_b32_e32 v0, s4
	s_waitcnt vmcnt(0) expcnt(0) lgkmcnt(0)
	ds_read_b32 v2, v0
	s_add_i32 s4, 0, 0x23fc4
	v_mov_b32_e32 v0, s4
	ds_read_b32 v0, v0
	s_waitcnt lgkmcnt(1)
	v_cmp_ne_u32_e32 vcc, 0, v2
	s_cbranch_vccnz .LBB0_585
	s_add_u32 s4, s62, 0x3300400
	s_addc_u32 s5, s63, 0
	s_add_u32 s6, s62, 0x3300500
	s_addc_u32 s7, s63, 0
	s_add_u32 s8, s62, 0x3300600
	s_addc_u32 s9, s63, 0
	s_add_u32 s10, s62, 0x3300700
	s_addc_u32 s11, s63, 0
	s_add_u32 s12, s62, 0x3300800
	s_addc_u32 s13, s63, 0
	s_add_u32 s14, s62, 0x3300900
	s_addc_u32 s15, s63, 0
	s_add_u32 s16, s62, 0x3300a00
	s_addc_u32 s17, s63, 0
	s_add_u32 s18, s62, 0x3300b00
	s_addc_u32 s19, s63, 0
	s_add_u32 s20, s62, 0x3300c00
	s_addc_u32 s21, s63, 0
	s_add_u32 s22, s62, 0x3300d00
	s_addc_u32 s23, s63, 0
	s_add_u32 s24, s62, 0x3300e00
	s_addc_u32 s25, s63, 0
	s_add_u32 s26, s62, 0x3300f00
	s_addc_u32 s27, s63, 0
	s_add_u32 s28, s62, 0x3301000
	s_addc_u32 s29, s63, 0
	s_add_u32 s30, s62, 0x3301100
	s_addc_u32 s31, s63, 0
	s_add_u32 s34, s62, 0x3301200
	s_addc_u32 s35, s63, 0
	s_mul_i32 s44, s83, s82
	s_add_u32 s36, s62, 0x3301300
	s_mul_i32 s44, s44, s90
	s_addc_u32 s37, s63, 0
	s_mov_b32 s45, 1
	v_mov_b32_e32 v16, 0
	s_branch .LBB0_573
